# stack: restructured softmax max chains, key fragment reads issued before the next-tile DMA block, both layers' shift GEMV items run concurrently in P0b
# baseline (speedup 1.0000x reference)
; #define INP(k) (args.in[lauint(k)])
; __global__ void __launch_bounds__(NWAVES * 64, 2) mega_fwd(Args args) {
;     ...
;     if (PH_ON(1)) {
;         const int l = 0; PTRS
; #pragma unroll 1
;         for (int l2 = 0; l2 < 2; ++l2) { const int l = l2;
;             float* shw = (float*)(ws + WS_SHW + (size_t)l * SHW_L); const float* ml = mods + (size_t)l * NB * NMOD;
;             for (int it = wave * G + vcu; it < (NGU + 4768 + NGU) / 32; it += NGW) {
;                 int n0 = it * 32;
;                 if (n0 < NGU) { const int dr = (n0 < FF) ? (n0 / 128) * 256 + (n0 % 128) : ((n0 - FF) / 128) * 256 + 128 + ((n0 - FF) % 128);
;                     sg_item(ml + 0 * DM, NMOD, false, INP(5) + (size_t)l * DM * NGU, NGU, n0, shw, NGU, dr, nullptr, lane); continue; }
;                 n0 -= NGU;
;                 if (n0 < 4768) { const int dr = (n0 < 1696) ? n0 : n0 + 96;
;                     sg_item(ml + 3 * DM, NMOD, false, INP(8) + (size_t)l * DM * 4768, 4768, n0, shw + 32 * NGU, NIN, dr, nullptr, lane); continue; }
;                 n0 -= 4768;
;                 { const int dr = (n0 < FF) ? (n0 / 128) * 256 + (n0 % 128) : ((n0 - FF) / 128) * 256 + 128 + ((n0 - FF) % 128);
;                     sg_item(ml + 6 * DM, NMOD, false, INP(22) + (size_t)l * DM * NGU, NGU, n0, shw + 32 * NGU + 32 * NIN, NGU, dr, nullptr, lane); }
;             }
;         }
.LBB0_122:
	s_or_b64 exec, exec, s[4:5]
	v_mov_b32_e32 v1, v228
	s_load_dwordx2 s[8:9], s[0:1], 0xd0
	s_barrier
	s_waitcnt lgkmcnt(0)
	s_load_dwordx2 s[4:5], s[0:1], 0xc8
	v_readfirstlane_b32 s3, v1
	s_ashr_i32 s3, s3, 6
	s_waitcnt lgkmcnt(0)
	s_add_u32 s4, s8, 0x300000
	v_writelane_b32 v254, s4, 9
	s_addc_u32 s4, s9, 0
	v_writelane_b32 v254, s4, 11
	v_writelane_b32 v254, s3, 12
	s_lshr_b32 s98, s3, 1
	s_and_b32 s3, s3, 1
	s_mul_i32 s3, s3, s44
	v_bfe_u32 v2, v1, 3, 3
	s_add_i32 s3, s3, s96
	s_lshr_b32 s99, s98, 1
	s_lshl_b32 s99, s99, 12
	s_add_i32 s3, s3, s99
	v_and_b32_e32 v0, 31, v1
	v_and_b32_e32 v6, 4, v2
	v_or_b32_e32 v9, 11, v2
	s_cmpk_lt_i32 s3, 0x1f5
	v_mul_u32_u24_e32 v7, 0x5800, v6
	v_or_b32_e32 v8, 3, v2
	v_mul_u32_u24_e32 v22, 0x1600, v9
	v_or_b32_e32 v11, 19, v2
	v_or_b32_e32 v2, 27, v2
	v_mul_u32_u24_e32 v10, 0x1300, v9
	v_lshlrev_b32_e32 v9, 2, v0
	v_writelane_b32 v254, s96, 14
	s_cselect_b64 s[4:5], -1, 0
	v_mul_u32_u24_e32 v4, 0x2400, v0
	v_mul_hi_u32_u24_e32 v3, 0x5800, v6
	v_mul_u32_u24_e32 v26, 0x1600, v2
	v_mul_u32_u24_e32 v14, 0x1300, v2
	v_or_b32_e32 v2, v7, v9
	s_mov_b64 s[6:7], 0x160000
	v_and_b32_e32 v21, 63, v1
	v_writelane_b32 v254, s4, 16
	v_lshl_add_u64 v[28:29], v[2:3], 0, s[6:7]
	v_lshrrev_b32_e32 v1, 1, v1
	v_lshlrev_b32_e32 v2, 2, v4
	v_writelane_b32 v254, s5, 17
	v_mov_b32_e32 v17, 0
	v_and_or_b32 v16, v1, 16, v2
	v_mul_u32_u24_e32 v13, 0x4a80, v6
	v_writelane_b32 v254, s3, 18
	s_lshl_b32 s3, s3, 5
	v_lshl_add_u64 v[2:3], s[8:9], 0, v[16:17]
	s_mov_b64 s[6:7], 0x61e0
	v_mul_hi_u32_u24_e32 v5, 0x4a80, v6
	s_add_i32 s4, s3, 0xffffd760
	v_lshl_add_u64 v[30:31], v[2:3], 0, s[6:7]
	v_or_b32_e32 v4, v13, v9
	s_mov_b64 s[6:7], 0x12a000
	v_writelane_b32 v254, s4, 19
	v_lshl_add_u64 v[32:33], v[4:5], 0, s[6:7]
	s_mov_b64 s[6:7], 0x31e0
	v_mul_u32_u24_e32 v18, 0x1600, v6
	v_mul_u32_u24_e32 v20, 0x1600, v8
	v_mul_u32_u24_e32 v6, 0x1300, v6
	v_mul_u32_u24_e32 v8, 0x1300, v8
	v_mul_u32_u24_e32 v12, 0x1300, v11
	v_writelane_b32 v254, s3, 20
	s_addk_i32 s3, 0xea00
	v_lshl_add_u64 v[34:35], v[2:3], 0, s[6:7]
	s_mov_b64 s[6:7], 0x1e0
	v_mul_u32_u24_e32 v24, 0x1600, v11
	v_writelane_b32 v254, s3, 22
	v_lshl_add_u64 v[36:37], v[2:3], 0, s[6:7]
	v_lshlrev_b32_e32 v38, 2, v0
	s_mov_b32 s41, 0xffea0000
	s_mov_b32 s42, 0xffea6000
	s_mov_b32 s43, 0xffeab000
	s_mov_b32 s46, 0xffeb1000
	s_mov_b32 s47, 0xffecc000
	s_mov_b32 s48, 0xffed2000
	s_mov_b32 s49, 0xffed7000
	s_mov_b32 s50, 0xffedd000
	s_mov_b32 s51, 0xffef8000
	s_mov_b32 s52, 0xffefe000
	s_mov_b32 s53, 0xfff03000
	s_mov_b32 s54, 0xfff09000
	s_mov_b32 s55, 0xfff24000
	s_mov_b32 s56, 0xfff2a000
	s_mov_b32 s57, 0xfff2f000
	s_mov_b32 s58, 0xfff35000
	s_mov_b32 s59, 0xfff50000
	s_mov_b32 s60, 0xfff56000
	s_mov_b32 s61, 0xfff5b000
	s_mov_b32 s62, 0xfff61000
	s_mov_b32 s63, 0xfff7c000
	s_mov_b32 s64, 0xfff82000
	s_mov_b32 s65, 0xfff87000
	s_mov_b32 s66, 0xfff8d000
	s_mov_b32 s67, 0xfffa8000
	s_mov_b32 s68, 0xfffae000
	s_mov_b32 s69, 0xfffb3000
	s_mov_b32 s70, 0xfffb9000
	s_mov_b32 s71, 0xfffd4000
	s_mov_b32 s72, 0xfffda000
	s_mov_b32 s73, 0xfffdf000
	s_mov_b32 s74, 0xfffe5000
	s_movk_i32 s75, 0x5000
	s_mov_b32 s76, 0xb000
	s_mov_b32 s77, 0x10000
	s_mov_b32 s78, 0x2c000
	s_mov_b32 s79, 0x31000
	s_mov_b32 s80, 0x37000
	s_mov_b32 s81, 0x3c000
	s_mov_b32 s82, 0x58000
	s_mov_b32 s83, 0x5d000
	s_mov_b32 s84, 0x63000
	s_mov_b32 s85, 0x68000
	s_mov_b32 s86, 0x84000
	s_mov_b32 s87, 0x89000
	s_mov_b32 s88, 0x8f000
	s_mov_b32 s89, 0x94000
	s_mov_b32 s90, 0xb0000
	s_mov_b32 s91, 0xb5000
	s_mov_b32 s92, 0xbb000
	s_mov_b32 s93, 0xc0000
	s_mov_b32 s94, 0xdc000
	s_mov_b32 s95, 0xe1000
	s_mov_b32 s96, 0xe7000
	s_mov_b32 s97, 0xec000
	s_mov_b32 s16, 0x108000
	s_mov_b32 s3, 0x10d000
	s_mov_b32 s33, 0x113000
	s_mov_b32 s34, 0x118000
	s_mov_b32 s35, 0x134000
	s_mov_b32 s39, 0x139000
	s_mov_b32 s40, 0x13f000
	s_mov_b32 s36, 0x144000
	v_lshlrev_b32_e32 v40, 2, v6
	v_lshlrev_b32_e32 v42, 2, v8
	v_lshlrev_b32_e32 v44, 2, v10
	v_lshlrev_b32_e32 v46, 2, v12
	v_lshlrev_b32_e32 v48, 2, v14
	s_mov_b32 s20, s98
	s_mov_b32 s21, 0
	s_mov_b64 s[10:11], 0
	s_mov_b32 s7, 0
	s_mov_b64 s[12:13], 0x2c0000
	s_mov_b64 s[14:15], 0x200
	s_branch .LBB0_124

; #define ATT_LAS __attribute__((address_space(3)))
; template <int DQK, int MODE> __device__ __forceinline__ void unit(const Desc& d, int q0, ATT_LAS char* shm, const float* biasg, float sinkl2) {
;     ...
;         asm volatile("s_waitcnt vmcnt(0) lgkmcnt(0)\n\ts_barrier" ::: "memory");
;         if (t + 1 < t1) ATT_DMA(t + 1, buf ^ 1);
;         const bool active = (MODE == 0) || (t >= wt0 && t < wt1);
;         if (active) {
;             f32x16 p0, p1;
;             { const ATT_LAS char* kb = shm + LDS_K + buf * KSLOT + hi * 1024 + r32 * 16;
; #pragma unroll
;               for (int d0 = 0; d0 < ND0; ++d0) {
;                   const bf16x8 b0 = *(const ATT_LAS bf16x8*)(kb + d0 * 2048);
;                   const bf16x8 b1 = *(const ATT_LAS bf16x8*)(kb + d0 * 2048 + 512);
;                   if (d0 == 0) { p0 = __builtin_amdgcn_mfma_f32_32x32x16_bf16(b0, qr[0], negm, 0, 0, 0); p1 = __builtin_amdgcn_mfma_f32_32x32x16_bf16(b1, qr[0], negm, 0, 0, 0); }
;                   else { p0 = __builtin_amdgcn_mfma_f32_32x32x16_bf16(b0, qr[d0], p0, 0, 0, 0); p1 = __builtin_amdgcn_mfma_f32_32x32x16_bf16(b1, qr[d0], p1, 0, 0, 0); } } }
.LBB0_540:
	s_waitcnt vmcnt(0) lgkmcnt(0)
	s_barrier
	s_lshl_b32 s41, s48, 13
	v_add_u32_e32 v0, s41, v124
	v_add_u32_e32 v234, s41, v126
	ds_read_b128 v[134:137], v0
	ds_read_b128 v[138:141], v0 offset:512
	ds_read_b128 v[142:145], v0 offset:2048
	ds_read_b128 v[146:149], v0 offset:2560
	ds_read_b128 v[150:153], v0 offset:4096
	ds_read_b128 v[154:157], v0 offset:4608
	ds_read_b128 v[158:161], v0 offset:6144
	ds_read_b128 v[162:165], v0 offset:6656
	v_mov_b32_e32 v224, s40
	v_mov_b32_e32 v225, s40
	v_mov_b32_e32 v226, s40
	v_mov_b32_e32 v227, s40
	s_cmp_lg_u32 s34, 0x690000
	s_mov_b64 s[36:37], -1
	s_cbranch_scc0 .LBB0_546
	s_lshl_b32 s41, s48, 13
	s_xor_b32 s36, s41, 0x2000
	s_and_b64 vcc, exec, s[4:5]
	s_add_i32 s37, s36, 0
	s_cbranch_vccnz .LBB0_543
	v_lshl_add_u64 v[66:67], v[118:119], 0, s[34:35]
	s_add_i32 s39, s37, s29
	s_mov_b32 s42, m0
	s_mov_b32 m0, s39
	s_nop 0
	global_load_lds_dwordx4 v[66:67], off
	s_mov_b32 m0, s42

; __device__ __forceinline__ float max3f(float a, float b, float c) { float r; asm("v_max3_f32 %0, %1, %2, %3" : "=v"(r) : "v"(a), "v"(b), "v"(c)); return r; }
; __device__ __forceinline__ float max2f(float a, float b) { float r; asm("v_max_f32_e32 %0, %1, %2" : "=v"(r) : "v"(a), "v"(b)); return r; }
; #define ATT_LAS __attribute__((address_space(3)))
; template <int DQK, int MODE> __device__ __forceinline__ void unit(const Desc& d, int q0, ATT_LAS char* shm, const float* biasg, float sinkl2) {
;     ...
;             { const ATT_LAS char* kb = shm + LDS_K + buf * KSLOT + hi * 1024 + r32 * 16;
; #pragma unroll
;               for (int d0 = 0; d0 < ND0; ++d0) {
;                   const bf16x8 b0 = *(const ATT_LAS bf16x8*)(kb + d0 * 2048);
;                   const bf16x8 b1 = *(const ATT_LAS bf16x8*)(kb + d0 * 2048 + 512);
;                   if (d0 == 0) { p0 = __builtin_amdgcn_mfma_f32_32x32x16_bf16(b0, qr[0], negm, 0, 0, 0); p1 = __builtin_amdgcn_mfma_f32_32x32x16_bf16(b1, qr[0], negm, 0, 0, 0); }
;                   else { p0 = __builtin_amdgcn_mfma_f32_32x32x16_bf16(b0, qr[d0], p0, 0, 0, 0); p1 = __builtin_amdgcn_mfma_f32_32x32x16_bf16(b1, qr[d0], p1, 0, 0, 0); } } }
;             if (MODE == 1) {
;                 const ATT_LAS float* bp = bias_l + (64 * t - (qw + r32) + 256 + 4 * hi);
; #pragma unroll
;                 for (int r = 0; r < 16; ++r) { p0[r] += bp[(r & 3) + 8 * (r >> 2)]; p1[r] += bp[(r & 3) + 8 * (r >> 2) + 32]; }
;             }
;             asm volatile("s_nop 15\n\ts_nop 7" : "+v"(p0), "+v"(p1));
;             float rm, rmb;
;             rm = max3f(p0[0], p0[1], p1[0]); rmb = max3f(p0[2], p0[3], p1[1]); rm = max3f(rm, p1[2], p1[3]);
; #pragma unroll
;             for (int r = 4; r < 16; r += 4) { rm = max3f(rm, p0[r], p0[r + 1]); rmb = max3f(rmb, p0[r + 2], p0[r + 3]); rm = max3f(rm, p1[r], p1[r + 1]); rmb = max3f(rmb, p1[r + 2], p1[r + 3]); }
;             rm = max2f(rm, rmb);
;             { auto rr = __builtin_amdgcn_permlane32_swap(__float_as_uint(rm), __float_as_uint(rm), false, false); rm = max2f(__uint_as_float(rr[0]), __uint_as_float(rr[1])); }
.LBB0_548:
	s_waitcnt lgkmcnt(7)
	v_mfma_f32_32x32x16_bf16 v[66:81], v[134:137], v[98:101], v[34:49]
	ds_read_b64_tr_b16 v[166:167], v234
	ds_read_b64_tr_b16 v[168:169], v234 offset:512
	s_waitcnt lgkmcnt(8)
	v_mfma_f32_32x32x16_bf16 v[82:97], v[138:141], v[98:101], v[34:49]
	ds_read_b64_tr_b16 v[170:171], v234 offset:1024
	ds_read_b64_tr_b16 v[172:173], v234 offset:1536
	s_waitcnt lgkmcnt(9)
	v_mfma_f32_32x32x16_bf16 v[66:81], v[142:145], v[102:105], v[66:81]
	ds_read_b64_tr_b16 v[174:175], v234 offset:2048
	ds_read_b64_tr_b16 v[176:177], v234 offset:2560
	s_waitcnt lgkmcnt(10)
	v_mfma_f32_32x32x16_bf16 v[82:97], v[146:149], v[102:105], v[82:97]
	ds_read_b64_tr_b16 v[178:179], v234 offset:3072
	ds_read_b64_tr_b16 v[180:181], v234 offset:3584
	s_waitcnt lgkmcnt(11)
	v_mfma_f32_32x32x16_bf16 v[66:81], v[150:153], v[106:109], v[66:81]
	ds_read_b64_tr_b16 v[182:183], v234 offset:4096
	ds_read_b64_tr_b16 v[184:185], v234 offset:4608
	s_waitcnt lgkmcnt(12)
	v_mfma_f32_32x32x16_bf16 v[82:97], v[154:157], v[106:109], v[82:97]
	ds_read_b64_tr_b16 v[186:187], v234 offset:5120
	ds_read_b64_tr_b16 v[188:189], v234 offset:5632
	s_waitcnt lgkmcnt(13)
	v_mfma_f32_32x32x16_bf16 v[66:81], v[158:161], v[110:113], v[66:81]
	ds_read_b64_tr_b16 v[190:191], v234 offset:6144
	ds_read_b64_tr_b16 v[192:193], v234 offset:6656
	s_waitcnt lgkmcnt(14)
	v_mfma_f32_32x32x16_bf16 v[82:97], v[162:165], v[110:113], v[82:97]
	ds_read_b64_tr_b16 v[194:195], v234 offset:7168
	ds_read_b64_tr_b16 v[196:197], v234 offset:7680
	s_nop 5
	v_max3_f32 v0, v66, v67, v68
	v_max3_f32 v129, v74, v75, v76
	v_max3_f32 v0, v0, v69, v70
	v_max3_f32 v129, v129, v77, v78
	v_max3_f32 v0, v0, v71, v72
	v_max3_f32 v129, v129, v79, v80
	v_max_f32_e32 v0, v0, v73
	v_max_f32_e32 v129, v129, v81
	v_max3_f32 v235, v82, v83, v84
	v_max3_f32 v236, v90, v91, v92
	v_max3_f32 v235, v235, v85, v86
	v_max3_f32 v236, v236, v93, v94
	v_max3_f32 v235, v235, v87, v88
	v_max3_f32 v236, v236, v95, v96
	v_max_f32_e32 v235, v235, v89
	v_max_f32_e32 v236, v236, v97
	v_max3_f32 v0, v0, v129, v235
	v_max_f32_e32 v0, v0, v236
	v_mov_b32_e32 v129, v0
	s_nop 1
	v_permlane32_swap_b32_e32 v0, v129
	v_max_f32_e32 v0, v0, v129
	v_cmp_lt_f32_e32 vcc, s70, v0
	s_cbranch_vccz .LBB0_539
	v_max_f32_e32 v0, v0, v0
	v_max_f32_e32 v0, 0, v0
	s_and_saveexec_b64 s[36:37], s[6:7]
	s_cbranch_execz .LBB0_538
	v_exp_f32_e64 v34, -v0
	ds_write_b32 v125, v34 offset:40960
	s_branch .LBB0_538

; #define ATT_LAS __attribute__((address_space(3)))
; template <int DQK, int MODE> __device__ __forceinline__ void unit(const Desc& d, int q0, ATT_LAS char* shm, const float* biasg, float sinkl2) {
;     ...
;         asm volatile("s_waitcnt vmcnt(0) lgkmcnt(0)\n\ts_barrier" ::: "memory");
;         if (t + 1 < t1) ATT_DMA(t + 1, buf ^ 1);
;         const bool active = (MODE == 0) || (t >= wt0 && t < wt1);
;         if (active) {
;             f32x16 p0, p1;
;             { const ATT_LAS char* kb = shm + LDS_K + buf * KSLOT + hi * 1024 + r32 * 16;
; #pragma unroll
;               for (int d0 = 0; d0 < ND0; ++d0) {
;                   const bf16x8 b0 = *(const ATT_LAS bf16x8*)(kb + d0 * 2048);
;                   const bf16x8 b1 = *(const ATT_LAS bf16x8*)(kb + d0 * 2048 + 512);
;                   if (d0 == 0) { p0 = __builtin_amdgcn_mfma_f32_32x32x16_bf16(b0, qr[0], negm, 0, 0, 0); p1 = __builtin_amdgcn_mfma_f32_32x32x16_bf16(b1, qr[0], negm, 0, 0, 0); }
;                   else { p0 = __builtin_amdgcn_mfma_f32_32x32x16_bf16(b0, qr[d0], p0, 0, 0, 0); p1 = __builtin_amdgcn_mfma_f32_32x32x16_bf16(b1, qr[d0], p1, 0, 0, 0); } } }
.LBB0_572:
	s_waitcnt vmcnt(0) lgkmcnt(0)
	s_barrier
	s_mul_i32 s39, s60, 0x3000
	v_add_u32_e32 v0, s39, v209
	v_add_u32_e32 v234, s39, v221
	v_add_u32_e32 v235, s39, v223
	v_add_u32_e32 v236, s39, v252
	v_add_u32_e32 v237, s39, v253
	ds_read_b128 v[130:133], v234
	ds_read_b128 v[134:137], v234 offset:4096
	ds_read_b128 v[138:141], v235
	ds_read_b128 v[142:145], v235 offset:4096
	ds_read_b128 v[146:149], v236
	ds_read_b128 v[150:153], v236 offset:4096
	ds_read_b128 v[154:157], v237
	ds_read_b128 v[158:161], v237 offset:4096
	ds_read_b128 v[162:165], v0 offset:8192
	ds_read_b128 v[166:169], v0 offset:8704
	ds_read_b128 v[170:173], v0 offset:10240
	ds_read_b128 v[174:177], v0 offset:10752
	v_mov_b32_e32 v224, s40
	v_mov_b32_e32 v225, s40
	v_mov_b32_e32 v226, s40
	v_mov_b32_e32 v227, s40
	s_add_i32 s61, s61, 1
	s_cmp_eq_u32 s96, 0x1f0000
	s_cbranch_scc1 .LBB0_586
	s_xor_b32 s39, s60, 1
	s_mulk_i32 s39, 0x3000
	v_lshl_or_b32 v0, s61, 6, v214
	s_andn2_b64 vcc, exec, s[30:31]
	s_add_i32 s39, s39, 0
	s_cbranch_vccnz .LBB0_579
	s_mov_b64 s[42:43], -1
	s_and_b64 vcc, exec, s[36:37]
	s_cbranch_vccz .LBB0_576
	v_mov_b64_e32 v[34:35], s[64:65]
	v_mad_u64_u32 v[34:35], s[42:43], v0, s73, v[34:35]
	v_lshl_add_u64 v[34:35], v[34:35], 0, s[92:93]
	s_mov_b64 s[42:43], 0

; #define ATT_LAS __attribute__((address_space(3)))
; template <int DQK, int MODE> __device__ __forceinline__ void unit(const Desc& d, int q0, ATT_LAS char* shm, const float* biasg, float sinkl2) {
;     ...
;             { const ATT_LAS char* kb = shm + LDS_K + buf * KSLOT + hi * 1024 + r32 * 16;
; #pragma unroll
;               for (int d0 = 0; d0 < ND0; ++d0) {
;                   const bf16x8 b0 = *(const ATT_LAS bf16x8*)(kb + d0 * 2048);
;                   const bf16x8 b1 = *(const ATT_LAS bf16x8*)(kb + d0 * 2048 + 512);
;                   if (d0 == 0) { p0 = __builtin_amdgcn_mfma_f32_32x32x16_bf16(b0, qr[0], negm, 0, 0, 0); p1 = __builtin_amdgcn_mfma_f32_32x32x16_bf16(b1, qr[0], negm, 0, 0, 0); }
;                   else { p0 = __builtin_amdgcn_mfma_f32_32x32x16_bf16(b0, qr[d0], p0, 0, 0, 0); p1 = __builtin_amdgcn_mfma_f32_32x32x16_bf16(b1, qr[d0], p1, 0, 0, 0); } } }
;             if (MODE == 1) {
;                 const ATT_LAS float* bp = bias_l + (64 * t - (qw + r32) + 256 + 4 * hi);
; #pragma unroll
;                 for (int r = 0; r < 16; ++r) { p0[r] += bp[(r & 3) + 8 * (r >> 2)]; p1[r] += bp[(r & 3) + 8 * (r >> 2) + 32]; }
;             }
;             asm volatile("s_nop 15\n\ts_nop 7" : "+v"(p0), "+v"(p1));
;             float rm, rmb;
;             rm = max3f(p0[0], p0[1], p1[0]); rmb = max3f(p0[2], p0[3], p1[1]); rm = max3f(rm, p1[2], p1[3]);
; #pragma unroll
;             for (int r = 4; r < 16; r += 4) { rm = max3f(rm, p0[r], p0[r + 1]); rmb = max3f(rmb, p0[r + 2], p0[r + 3]); rm = max3f(rm, p1[r], p1[r + 1]); rmb = max3f(rmb, p1[r + 2], p1[r + 3]); }
;             rm = max2f(rm, rmb);
;             { auto rr = __builtin_amdgcn_permlane32_swap(__float_as_uint(rm), __float_as_uint(rm), false, false); rm = max2f(__uint_as_float(rr[0]), __uint_as_float(rr[1])); }
;             const bool first = (t == wt0);
;             if (first) {
;                 mhat = rm;
; #pragma unroll
;                 for (int r = 0; r < 16; ++r) { p0[r] -= rm; p1[r] -= rm; }
; #pragma unroll
;                 for (int r = 0; r < 16; ++r) negm[r] = -mhat;
;             } else if (__any(rm > THR)) {
;                 const float dl = fmaxf(rm, 0.f); mhat += dl;
; #pragma unroll
;                 for (int r = 0; r < 16; ++r) { p0[r] -= dl; p1[r] -= dl; }
; #pragma unroll
;                 for (int r = 0; r < 16; ++r) negm[r] = -mhat;
.LBB0_586:
	v_lshl_add_u32 v0, s60, 13, v219
	s_waitcnt lgkmcnt(11)
	v_mfma_f32_32x32x16_bf16 v[114:129], v[130:133], v[178:181], v[66:81]
	ds_read_b64_tr_b16 v[34:35], v0
	s_waitcnt lgkmcnt(11)
	v_mfma_f32_32x32x16_bf16 v[98:113], v[134:137], v[178:181], v[66:81]
	ds_read_b64_tr_b16 v[36:37], v0 offset:512
	s_waitcnt lgkmcnt(11)
	v_mfma_f32_32x32x16_bf16 v[114:129], v[138:141], v[182:185], v[114:129]
	ds_read_b64_tr_b16 v[38:39], v0 offset:1024
	s_waitcnt lgkmcnt(11)
	v_mfma_f32_32x32x16_bf16 v[98:113], v[142:145], v[182:185], v[98:113]
	ds_read_b64_tr_b16 v[40:41], v0 offset:1536
	s_waitcnt lgkmcnt(11)
	v_mfma_f32_32x32x16_bf16 v[114:129], v[146:149], v[186:189], v[114:129]
	ds_read_b64_tr_b16 v[42:43], v0 offset:2048
	s_waitcnt lgkmcnt(11)
	v_mfma_f32_32x32x16_bf16 v[98:113], v[150:153], v[186:189], v[98:113]
	ds_read_b64_tr_b16 v[44:45], v0 offset:2560
	s_waitcnt lgkmcnt(11)
	v_mfma_f32_32x32x16_bf16 v[114:129], v[154:157], v[190:193], v[114:129]
	ds_read_b64_tr_b16 v[46:47], v0 offset:3072
	s_waitcnt lgkmcnt(11)
	v_mfma_f32_32x32x16_bf16 v[98:113], v[158:161], v[190:193], v[98:113]
	ds_read_b64_tr_b16 v[48:49], v0 offset:3584
	s_waitcnt lgkmcnt(11)
	v_mfma_f32_32x32x16_bf16 v[114:129], v[162:165], v[194:197], v[114:129]
	ds_read_b64_tr_b16 v[50:51], v0 offset:4096
	s_waitcnt lgkmcnt(11)
	v_mfma_f32_32x32x16_bf16 v[98:113], v[166:169], v[194:197], v[98:113]
	ds_read_b64_tr_b16 v[52:53], v0 offset:4608
	s_waitcnt lgkmcnt(11)
	v_mfma_f32_32x32x16_bf16 v[114:129], v[170:173], v[198:201], v[114:129]
	ds_read_b64_tr_b16 v[54:55], v0 offset:5120
	s_waitcnt lgkmcnt(11)
	v_mfma_f32_32x32x16_bf16 v[98:113], v[174:177], v[198:201], v[98:113]
	ds_read_b64_tr_b16 v[56:57], v0 offset:5632
	ds_read_b64_tr_b16 v[58:59], v0 offset:6144
	ds_read_b64_tr_b16 v[60:61], v0 offset:6656
	ds_read_b64_tr_b16 v[62:63], v0 offset:7168
	ds_read_b64_tr_b16 v[64:65], v0 offset:7680
	s_nop 4
	v_max3_f32 v0, v114, v115, v116
	v_max3_f32 v222, v122, v123, v124
	v_max3_f32 v0, v0, v117, v118
	v_max3_f32 v222, v222, v125, v126
	v_max3_f32 v0, v0, v119, v120
	v_max3_f32 v222, v222, v127, v128
	v_max_f32_e32 v0, v0, v121
	v_max_f32_e32 v222, v222, v129
	v_max3_f32 v246, v98, v99, v100
	v_max3_f32 v247, v106, v107, v108
	v_max3_f32 v246, v246, v101, v102
	v_max3_f32 v247, v247, v109, v110
	v_max3_f32 v246, v246, v103, v104
	v_max3_f32 v247, v247, v111, v112
	v_max_f32_e32 v246, v246, v105
	v_max_f32_e32 v247, v247, v113
	v_max3_f32 v0, v0, v222, v246
	v_max_f32_e32 v0, v0, v247
	v_mov_b32_e32 v222, v0
	s_nop 1
	v_permlane32_swap_b32_e32 v0, v222
	v_max_f32_e32 v0, v0, v222
	s_cmp_lg_u32 s96, 0
	s_cbranch_scc0 .LBB0_591
	v_cmp_lt_f32_e32 vcc, s70, v0
	s_cbranch_vccz .LBB0_571
	v_max_f32_e32 v250, v0, v0
	v_max_f32_e32 v250, 0, v250
	s_and_saveexec_b64 s[42:43], s[4:5]
	v_exp_f32_e64 v251, -v250
	s_nop 0
	ds_write_b32 v218, v251 offset:40960
	s_or_b64 exec, exec, s[42:43]
	s_waitcnt lgkmcnt(0)
	v_add_u32_e32 v251, s54, v208
	ds_read_b128 v[234:237], v251 offset:40960
	ds_read_b128 v[238:241], v251 offset:40992
	ds_read_b128 v[242:245], v251 offset:41024
	ds_read_b128 v[246:249], v251 offset:41056
	v_add_f32_e32 v220, v220, v250
	v_xor_b32_e32 v81, 0x80000000, v220
	v_sub_f32_e32 v114, v114, v250
	v_sub_f32_e32 v115, v115, v250
	v_sub_f32_e32 v116, v116, v250
	v_sub_f32_e32 v117, v117, v250
	v_sub_f32_e32 v118, v118, v250
	v_sub_f32_e32 v119, v119, v250
	v_sub_f32_e32 v120, v120, v250
	v_sub_f32_e32 v121, v121, v250
	v_sub_f32_e32 v122, v122, v250
	v_sub_f32_e32 v123, v123, v250
	v_sub_f32_e32 v124, v124, v250
	v_sub_f32_e32 v125, v125, v250
	v_sub_f32_e32 v126, v126, v250
	v_sub_f32_e32 v127, v127, v250
	v_sub_f32_e32 v128, v128, v250
	v_sub_f32_e32 v129, v129, v250
	v_sub_f32_e32 v98, v98, v250
	v_sub_f32_e32 v99, v99, v250
	v_sub_f32_e32 v100, v100, v250
	v_sub_f32_e32 v101, v101, v250
	v_sub_f32_e32 v102, v102, v250
	v_sub_f32_e32 v103, v103, v250
	v_sub_f32_e32 v104, v104, v250
	v_sub_f32_e32 v105, v105, v250
	v_sub_f32_e32 v106, v106, v250
	v_sub_f32_e32 v107, v107, v250
	v_sub_f32_e32 v108, v108, v250
	v_sub_f32_e32 v109, v109, v250
	v_sub_f32_e32 v110, v110, v250
	v_sub_f32_e32 v111, v111, v250
	v_sub_f32_e32 v112, v112, v250
	v_sub_f32_e32 v113, v113, v250
	s_waitcnt lgkmcnt(0)
	v_pk_mul_f32 v[2:3], v[2:3], v[234:235]
	v_pk_mul_f32 v[4:5], v[4:5], v[236:237]
	v_pk_mul_f32 v[6:7], v[6:7], v[238:239]
	v_pk_mul_f32 v[8:9], v[8:9], v[240:241]
	v_pk_mul_f32 v[10:11], v[10:11], v[242:243]
	v_pk_mul_f32 v[12:13], v[12:13], v[244:245]
	v_pk_mul_f32 v[14:15], v[14:15], v[246:247]
	v_pk_mul_f32 v[16:17], v[16:17], v[248:249]
	v_pk_mul_f32 v[18:19], v[18:19], v[234:235]
	v_pk_mul_f32 v[20:21], v[20:21], v[236:237]
	v_pk_mul_f32 v[22:23], v[22:23], v[238:239]
	v_pk_mul_f32 v[24:25], v[24:25], v[240:241]
	v_pk_mul_f32 v[26:27], v[26:27], v[242:243]
	v_pk_mul_f32 v[28:29], v[28:29], v[244:245]
	v_pk_mul_f32 v[30:31], v[30:31], v[246:247]
	v_pk_mul_f32 v[32:33], v[32:33], v[248:249]
	v_pk_mul_f32 v[82:83], v[82:83], v[234:235]
	v_pk_mul_f32 v[84:85], v[84:85], v[236:237]
	v_pk_mul_f32 v[86:87], v[86:87], v[238:239]
	v_pk_mul_f32 v[88:89], v[88:89], v[240:241]
	v_pk_mul_f32 v[90:91], v[90:91], v[242:243]
	v_pk_mul_f32 v[92:93], v[92:93], v[244:245]
	v_pk_mul_f32 v[94:95], v[94:95], v[246:247]
	v_pk_mul_f32 v[96:97], v[96:97], v[248:249]
	v_mov_b32_e32 v80, v81
	v_mov_b32_e32 v79, v81
	v_mov_b32_e32 v78, v81
	v_mov_b32_e32 v77, v81
	v_mov_b32_e32 v76, v81
	v_mov_b32_e32 v75, v81
	v_mov_b32_e32 v74, v81
	v_mov_b32_e32 v73, v81
	v_mov_b32_e32 v72, v81
	v_mov_b32_e32 v71, v81
	v_mov_b32_e32 v70, v81
	v_mov_b32_e32 v69, v81
	v_mov_b32_e32 v68, v81
	v_mov_b32_e32 v67, v81
	v_mov_b32_e32 v66, v81
	s_branch .LBB0_571

; __global__ void __launch_bounds__(NWAVES * 64, 2) mega_fwd(Args args) {
	.amdhsa_kernel _Z8mega_fwd4Args
		.amdhsa_group_segment_fixed_size 0
		.amdhsa_private_segment_fixed_size 0
		.amdhsa_kernarg_size 472
		.amdhsa_user_sgpr_count 2
		.amdhsa_user_sgpr_dispatch_ptr 0
		.amdhsa_user_sgpr_queue_ptr 0
		.amdhsa_user_sgpr_kernarg_segment_ptr 1
		.amdhsa_user_sgpr_dispatch_id 0
		.amdhsa_user_sgpr_kernarg_preload_length 0
		.amdhsa_user_sgpr_kernarg_preload_offset 0
		.amdhsa_user_sgpr_private_segment_size 0
		.amdhsa_uses_dynamic_stack 0
		.amdhsa_enable_private_segment 0
		.amdhsa_system_sgpr_workgroup_id_x 1
		.amdhsa_system_sgpr_workgroup_id_y 0
		.amdhsa_system_sgpr_workgroup_id_z 0
		.amdhsa_system_sgpr_workgroup_info 0
		.amdhsa_system_vgpr_workitem_id 2
		.amdhsa_next_free_vgpr 256
		.amdhsa_next_free_sgpr 102
		.amdhsa_accum_offset 256
		.amdhsa_reserve_vcc 1
		.amdhsa_float_round_mode_32 0
		.amdhsa_float_round_mode_16_64 0
		.amdhsa_float_denorm_mode_32 3
		.amdhsa_float_denorm_mode_16_64 3
		.amdhsa_dx10_clamp 1
		.amdhsa_ieee_mode 1
		.amdhsa_fp16_overflow 0
		.amdhsa_tg_split 0
		.amdhsa_exception_fp_ieee_invalid_op 0
		.amdhsa_exception_fp_denorm_src 0
		.amdhsa_exception_fp_ieee_div_zero 0
		.amdhsa_exception_fp_ieee_overflow 0
		.amdhsa_exception_fp_ieee_underflow 0
		.amdhsa_exception_fp_ieee_inexact 0
		.amdhsa_exception_int_div_zero 0
	.end_amdhsa_kernel

; __global__ void __launch_bounds__(NWAVES * 64, 2) mega_fwd(Args args) {
amdhsa.kernels:
  - .agpr_count:     0
    .args:
      - .offset:         0
        .size:           216
        .value_kind:     by_value
      - .offset:         216
        .size:           4
        .value_kind:     hidden_block_count_x
      - .offset:         220
        .size:           4
        .value_kind:     hidden_block_count_y
      - .offset:         224
        .size:           4
        .value_kind:     hidden_block_count_z
      - .offset:         228
        .size:           2
        .value_kind:     hidden_group_size_x
      - .offset:         230
        .size:           2
        .value_kind:     hidden_group_size_y
      - .offset:         232
        .size:           2
        .value_kind:     hidden_group_size_z
      - .offset:         234
        .size:           2
        .value_kind:     hidden_remainder_x
      - .offset:         236
        .size:           2
        .value_kind:     hidden_remainder_y
      - .offset:         238
        .size:           2
        .value_kind:     hidden_remainder_z
      - .offset:         256
        .size:           8
        .value_kind:     hidden_global_offset_x
      - .offset:         264
        .size:           8
        .value_kind:     hidden_global_offset_y
      - .offset:         272
        .size:           8
        .value_kind:     hidden_global_offset_z
      - .offset:         280
        .size:           2
        .value_kind:     hidden_grid_dims
      - .offset:         304
        .size:           8
        .value_kind:     hidden_multigrid_sync_arg
      - .offset:         336
        .size:           4
        .value_kind:     hidden_dynamic_lds_size
    .group_segment_fixed_size: 0
    .kernarg_segment_align: 8
    .kernarg_segment_size: 472
    .language:       OpenCL C
    .language_version:
      - 2
      - 0
    .max_flat_workgroup_size: 512
    .name:           _Z8mega_fwd4Args
    .private_segment_fixed_size: 0
    .sgpr_count:     108
    .sgpr_spill_count: 87
    .symbol:         _Z8mega_fwd4Args.kd
    .uniform_work_group_size: 1
    .uses_dynamic_stack: false
    .vgpr_count:     256
    .vgpr_spill_count: 0
    .wavefront_size: 64
